# up-proj epilogue: ACT stores of six row groups merged to 16 B via permlane16_swap (n=0 piece held in registers)
# speedup vs baseline: 1.0282x; 1.0029x over previous
; __device__ __forceinline__ int otid() { int t = threadIdx.x; asm volatile("" : "+v"(t)); return t; }
;     __device__ __forceinline__ void operator()(const f32x4 (&acc)[2][2][4][2], const Unit& u, int wr, int wc, int fr, int fq) const {
;     ...
;         const int lane = otid() & 63;
;         const int src1 = (lane & 48) | ((fr + 15) & 15), src2 = (lane & 48) | ((fr + 14) & 15);
;         float rs[2][4];
; #pragma unroll
;         for (int ai = 0; ai < 2; ++ai)
; #pragma unroll
;             for (int m = 0; m < 4; ++m) rs[ai][m] = __builtin_amdgcn_rsqf((float)ss[u.pm * BM + ai * HALF + wr * 64 + m * 16 + fr] * (1.f / (2048.f * 262144.f)) + 1e-6f);
; #pragma unroll
;         for (int n = 0; n < 2; ++n) {
;             const int cbase = 128 * u.pn + 32 * wc + 16 * n + 4 * fq;
;             const f32x4 w0 = *(const f32x4*)(cw + cbase), w1 = *(const f32x4*)(cw + FF + cbase), w2 = *(const f32x4*)(cw + 2 * FF + cbase), b4 = *(const f32x4*)(cb + cbase);
; #pragma unroll
;             for (int ai = 0; ai < 2; ++ai) {
;                 const int slab = u.pm * 4 + 2 * ai + wr;
;                 f32x4 r1p = (f32x4){0.f, 0.f, 0.f, 0.f}, r2p = (f32x4){0.f, 0.f, 0.f, 0.f};
; #pragma unroll
;                 for (int m = 0; m < 4; ++m) {
;                     const f32x4 g = acc[ai][1][m][n] * rs[ai][m], v = acc[ai][0][m][n] * rs[ai][m];
;                     f32x4 r1, r2, a;
; #pragma unroll
;                     for (int e = 0; e < 4; ++e) { r1[e] = __shfl(g[e], src1); r2[e] = __shfl(g[e], src2); }
; #pragma unroll
;                     for (int e = 0; e < 4; ++e) {
;                         const float p1 = fr >= 1 ? r1[e] : r1p[e], p2 = fr >= 2 ? r2[e] : r2p[e];
;                         const float gg = b4[e] + w0[e] * p2 + w1[e] * p1 + w2[e] * g[e];
;                         a[e] = gg * __builtin_amdgcn_rcpf(1.f + __expf(-gg)) * v[e];
;                     }
;                     r1p = r1; r2p = r2;
;                     const size_t row = (size_t)(u.pm * BM + ai * HALF + wr * 64 + m * 16 + fr);
;                     if (m == 0 && fr < 2) {
;                         *(f32x4*)(GF + (size_t)(slab * 2 + fr) * FF + cbase) = g; *(f32x4*)(VF + (size_t)(slab * 2 + fr) * FF + cbase) = v;
.LBB0_41:
	v_lshl_add_u32 v160, s66, 8, v193
	v_ashrrev_i32_e32 v161, 31, v160
	v_mov_b32_e32 v148, v227
	v_bfe_u32 v205, v227, 4, 1
	v_mul_u32_u24_e32 v205, 24, v205
	v_lshl_add_u64 v[114:115], v[160:161], 3, s[56:57]
	global_load_dwordx2 v[146:147], v[114:115], off
	v_lshl_or_b32 v156, s64, 7, v198
	v_ashrrev_i32_e32 v157, 31, v156
	global_load_dwordx2 v[190:191], v[114:115], off offset:128
	global_load_dwordx2 v[188:189], v[114:115], off offset:256
	global_load_dwordx2 v[186:187], v[114:115], off offset:384
	global_load_dwordx2 v[176:177], v[114:115], off offset:1024
	global_load_dwordx2 v[174:175], v[114:115], off offset:1152
	global_load_dwordx2 v[172:173], v[114:115], off offset:1280
	global_load_dwordx2 v[170:171], v[114:115], off offset:1408
	v_lshlrev_b64 v[158:159], 2, v[156:157]
	v_lshl_add_u64 v[166:167], s[52:53], 0, v[158:159]
	v_lshl_add_u64 v[118:119], s[60:61], 0, v[158:159]
	v_lshl_add_u64 v[120:121], s[62:63], 0, v[158:159]
	v_lshl_add_u64 v[164:165], s[54:55], 0, v[158:159]
	global_load_dwordx4 v[114:117], v[166:167], off
	global_load_dwordx4 v[138:141], v[118:119], off
	global_load_dwordx4 v[130:133], v[120:121], off
	s_nop 0
	global_load_dwordx4 v[118:121], v[164:165], off
	s_waitcnt vmcnt(0)
	v_ffbh_u32_e32 v149, v147
	v_min_u32_e32 v149, 32, v149
	v_lshlrev_b64 v[146:147], v149, v[146:147]
	v_min_u32_e32 v146, 1, v146
	v_or_b32_e32 v146, v147, v146
	v_cvt_f32_u32_e32 v146, v146
	v_sub_u32_e32 v149, 32, v149
	v_and_b32_e32 v147, 48, v148
	v_or3_b32 v148, v147, v195, v236
	v_ldexp_f32 v146, v146, v149
	v_fmamk_f32 v146, v146, 0x31000000, v232
	v_rsq_f32_e32 v162, v146
	v_or3_b32 v146, v147, v196, v236
	v_lshlrev_b32_e32 v200, 2, v146
	v_lshlrev_b32_e32 v161, 2, v148
	v_pk_mul_f32 v[146:147], v[134:135], v[162:163] op_sel_hi:[1,0]
	v_pk_mul_f32 v[148:149], v[136:137], v[162:163] op_sel_hi:[1,0]
	ds_bpermute_b32 v163, v200, v146
	ds_bpermute_b32 v179, v161, v146
	ds_bpermute_b32 v181, v161, v147
	ds_bpermute_b32 v201, v200, v147
	ds_bpermute_b32 v183, v161, v148
	ds_bpermute_b32 v202, v200, v148
	ds_bpermute_b32 v185, v161, v149
	ds_bpermute_b32 v203, v200, v149
	s_waitcnt lgkmcnt(7)
	v_pk_mul_f32 v[136:137], v[144:145], v[162:163] op_sel_hi:[1,0]
	v_pk_mul_f32 v[134:135], v[142:143], v[162:163] op_sel_hi:[1,0]
	s_and_saveexec_b64 s[10:11], s[42:43]
	s_xor_b64 s[10:11], exec, s[10:11]
	s_movk_i32 s17, 0x2b00
	s_movk_i32 s84, 0x300
	s_mov_b32 s86, 0x24000
	s_mov_b32 s88, 0x48800000
	s_cbranch_execz .LBB0_43
	v_mov_b32_e32 v142, v149
	v_mov_b32_e32 v143, v141
	v_mov_b32_e32 v184, v133
	s_waitcnt lgkmcnt(1)
	v_pk_mul_f32 v[142:143], v[142:143], v[184:185]
	s_waitcnt lgkmcnt(0)
	v_fma_f32 v144, v117, v203, v121
	v_add_f32_e32 v143, v143, v144
	v_add_f32_e32 v142, v142, v143
	v_mul_f32_e32 v143, 0xbfb8aa3b, v142
	v_exp_f32_e32 v143, v143
	v_mov_b32_e32 v149, v140
	v_mov_b32_e32 v182, v132
	v_mov_b32_e32 v180, v131
	v_add_f32_e32 v143, 1.0, v143
	v_rcp_f32_e32 v143, v143
	v_mov_b32_e32 v178, v130
	v_mul_f32_e32 v142, v142, v143
	v_mul_f32_e32 v144, v137, v142
	v_pk_mul_f32 v[142:143], v[148:149], v[182:183]
	v_fma_f32 v137, v116, v202, v120
	v_add_f32_e32 v137, v143, v137
	v_add_f32_e32 v137, v142, v137
	v_mul_f32_e32 v142, 0xbfb8aa3b, v137
	v_exp_f32_e32 v142, v142
	v_fma_f32 v143, v115, v201, v119
	v_add_f32_e32 v142, 1.0, v142
	v_rcp_f32_e32 v142, v142
	s_nop 0
	v_mul_f32_e32 v137, v137, v142
	v_mul_f32_e32 v142, v136, v137
	v_mov_b32_e32 v136, v147
	v_mov_b32_e32 v137, v139
	v_pk_mul_f32 v[136:137], v[136:137], v[180:181]
	v_mov_b32_e32 v147, v138
	v_add_f32_e32 v137, v137, v143
	v_add_f32_e32 v136, v136, v137
	v_mul_f32_e32 v137, 0xbfb8aa3b, v136
	v_exp_f32_e32 v137, v137
	v_fma_f32 v143, v114, v163, v118
	v_add_f32_e32 v137, 1.0, v137
	v_rcp_f32_e32 v137, v137
	s_nop 0
	v_mul_f32_e32 v136, v136, v137
	v_mul_f32_e32 v135, v135, v136
	v_pk_mul_f32 v[136:137], v[146:147], v[178:179]
	s_nop 0
	v_add_f32_e32 v137, v137, v143
	v_add_f32_e32 v136, v136, v137
	v_mul_f32_e32 v137, 0xbfb8aa3b, v136
	v_exp_f32_e32 v137, v137
	s_nop 0
	v_add_f32_e32 v137, 1.0, v137
	v_rcp_f32_e32 v137, v137
	s_nop 0
	v_mul_f32_e32 v136, v136, v137
	v_mul_f32_e32 v134, v134, v136
	v_mov_b64_e32 v[136:137], s[48:49]
	v_mad_i64_i32 v[136:137], s[12:13], v160, s17, v[136:137]
	v_cvt_pk_bf16_f32 v134, v134, v135
	v_cvt_pk_bf16_f32 v135, v142, v144
	v_lshl_add_u64 v[136:137], v[156:157], 1, v[136:137]
	global_store_dwordx2 v[136:137], v[134:135], off

; __device__ __forceinline__ unsigned cvt_pk_bf16(float lo, float hi) { unsigned r; asm volatile("v_cvt_pk_bf16_f32 %0, %1, %2" : "=v"(r) : "v"(lo), "v"(hi)); return r; }
;     __device__ __forceinline__ void operator()(const f32x4 (&acc)[2][2][4][2], const Unit& u, int wr, int wc, int fr, int fq) const {
;     ...
;                 for (int m = 0; m < 4; ++m) {
;                     const f32x4 g = acc[ai][1][m][n] * rs[ai][m], v = acc[ai][0][m][n] * rs[ai][m];
;                     f32x4 r1, r2, a;
; #pragma unroll
;                     for (int e = 0; e < 4; ++e) { r1[e] = __shfl(g[e], src1); r2[e] = __shfl(g[e], src2); }
; #pragma unroll
;                     for (int e = 0; e < 4; ++e) {
;                         const float p1 = fr >= 1 ? r1[e] : r1p[e], p2 = fr >= 2 ? r2[e] : r2p[e];
;                         const float gg = b4[e] + w0[e] * p2 + w1[e] * p1 + w2[e] * g[e];
;                         a[e] = gg * __builtin_amdgcn_rcpf(1.f + __expf(-gg)) * v[e];
;                     }
;                     r1p = r1; r2p = r2;
;                     const size_t row = (size_t)(u.pm * BM + ai * HALF + wr * 64 + m * 16 + fr);
;                     if (m == 0 && fr < 2) {
;                         *(f32x4*)(GF + (size_t)(slab * 2 + fr) * FF + cbase) = g; *(f32x4*)(VF + (size_t)(slab * 2 + fr) * FF + cbase) = v;
;                     } else {
;                         typedef unsigned u32x2v __attribute__((ext_vector_type(2)));
;                         u32x2v w; w.x = cvt_pk_bf16(a[0], a[1]); w.y = cvt_pk_bf16(a[2], a[3]);
;                         *(u32x2v*)(ACT + row * FF + cbase) = w;
.LBB0_45:
	s_or_b64 exec, exec, s[10:11]
	s_nop 0
	v_ffbh_u32_e32 v134, v191
	v_min_u32_e32 v136, 32, v134
	v_lshlrev_b64 v[134:135], v136, v[190:191]
	v_min_u32_e32 v134, 1, v134
	v_or_b32_e32 v134, v135, v134
	v_cvt_f32_u32_e32 v134, v134
	v_ffbh_u32_e32 v135, v189
	v_sub_u32_e32 v136, 32, v136
	v_min_u32_e32 v143, 32, v135
	v_ldexp_f32 v134, v134, v136
	v_fmamk_f32 v136, v134, 0x31000000, v232
	v_lshlrev_b64 v[134:135], v143, v[188:189]
	v_min_u32_e32 v134, 1, v134
	v_or_b32_e32 v134, v135, v134
	v_cvt_f32_u32_e32 v134, v134
	v_sub_u32_e32 v135, 32, v143
	v_rsq_f32_e32 v142, v136
	v_mov_b32_e32 v149, v141
	v_ldexp_f32 v134, v134, v135
	v_fmamk_f32 v136, v134, 0x31000000, v232
	v_ffbh_u32_e32 v134, v187
	v_min_u32_e32 v143, 32, v134
	v_lshlrev_b64 v[134:135], v143, v[186:187]
	v_min_u32_e32 v134, 1, v134
	v_or_b32_e32 v134, v135, v134
	v_cvt_f32_u32_e32 v134, v134
	v_sub_u32_e32 v143, 32, v143
	s_movk_i32 s10, 0x5600
	v_rsq_f32_e32 v136, v136
	v_ldexp_f32 v134, v134, v143
	v_add_u32_e32 v143, s12, v197
	v_pk_mul_f32 v[128:129], v[128:129], v[142:143] op_sel_hi:[1,0]
	ds_bpermute_b32 v186, v161, v129
	ds_bpermute_b32 v191, v200, v129
	v_mov_b32_e32 v148, v129
	v_pk_mul_f32 v[126:127], v[126:127], v[142:143] op_sel_hi:[1,0]
	v_mad_i64_i32 v[146:147], s[10:11], v143, s10, 0
	s_waitcnt lgkmcnt(1)
	v_cndmask_b32_e64 v185, v186, v185, s[40:41]
	s_waitcnt lgkmcnt(0)
	v_cndmask_b32_e64 v129, v203, v191, s[42:43]
	v_pk_mul_f32 v[148:149], v[148:149], v[184:185]
	v_fma_f32 v129, v117, v129, v121
	v_add_f32_e32 v129, v149, v129
	v_add_f32_e32 v148, v148, v129
	v_mul_f32_e32 v129, 0xbfb8aa3b, v148
	v_exp_f32_e32 v129, v129
	ds_bpermute_b32 v149, v161, v128
	ds_bpermute_b32 v203, v200, v128
	ds_bpermute_b32 v143, v161, v126
	v_add_f32_e32 v129, 1.0, v129
	v_rcp_f32_e32 v185, v129
	s_waitcnt lgkmcnt(2)
	v_cndmask_b32_e64 v183, v149, v183, s[40:41]
	v_mov_b32_e32 v129, v140
	v_pk_mul_f32 v[128:129], v[128:129], v[182:183]
	s_waitcnt lgkmcnt(1)
	v_cndmask_b32_e64 v183, v202, v203, s[42:43]
	v_fma_f32 v183, v116, v183, v120
	v_add_f32_e32 v129, v129, v183
	v_add_f32_e32 v183, v128, v129
	v_mul_f32_e32 v128, 0xbfb8aa3b, v183
	ds_bpermute_b32 v189, v161, v127
	ds_bpermute_b32 v190, v200, v127
	v_exp_f32_e32 v128, v128
	s_waitcnt lgkmcnt(2)
	v_pk_mul_f32 v[124:125], v[124:125], v[142:143] op_sel_hi:[1,0]
	v_mul_f32_e32 v129, v148, v185
	ds_bpermute_b32 v187, v200, v126
	v_add_f32_e32 v128, 1.0, v128
	v_mul_f32_e32 v125, v125, v129
	v_rcp_f32_e32 v148, v128
	s_waitcnt lgkmcnt(2)
	v_cndmask_b32_e64 v181, v189, v181, s[40:41]
	v_mov_b32_e32 v128, v127
	v_mov_b32_e32 v129, v139
	s_waitcnt lgkmcnt(1)
	v_cndmask_b32_e64 v127, v201, v190, s[42:43]
	v_pk_mul_f32 v[128:129], v[128:129], v[180:181]
	v_fma_f32 v127, v115, v127, v119
	v_add_f32_e32 v127, v129, v127
	v_add_f32_e32 v128, v128, v127
	v_mul_f32_e32 v127, 0xbfb8aa3b, v128
	v_exp_f32_e32 v129, v127
	v_cndmask_b32_e64 v179, v143, v179, s[40:41]
	v_mov_b32_e32 v127, v138
	s_waitcnt lgkmcnt(0)
	v_cndmask_b32_e64 v163, v163, v187, s[42:43]
	v_pk_mul_f32 v[126:127], v[126:127], v[178:179]
	v_fma_f32 v163, v114, v163, v118
	v_add_f32_e32 v127, v127, v163
	v_add_f32_e32 v126, v126, v127
	v_mul_f32_e32 v127, 0xbfb8aa3b, v126
	v_exp_f32_e32 v127, v127
	v_add_f32_e32 v129, 1.0, v129
	v_rcp_f32_e32 v129, v129
	v_or_b32_e32 v137, 16, v160
	v_add_f32_e32 v127, 1.0, v127
	v_rcp_f32_e32 v127, v127
	v_mul_f32_e32 v148, v183, v148
	v_pk_mul_f32 v[112:113], v[112:113], v[136:137] op_sel_hi:[1,0]
	v_mul_f32_e32 v124, v124, v148
	ds_bpermute_b32 v148, v161, v113
	ds_bpermute_b32 v204, v200, v113
	v_pk_mul_f32 v[122:123], v[122:123], v[142:143] op_sel_hi:[1,0]
	v_mul_f32_e32 v128, v128, v129
	v_mul_f32_e32 v126, v126, v127
	v_mul_f32_e32 v123, v123, v128
	v_mul_f32_e32 v122, v122, v126
	v_mov_b64_e32 v[128:129], s[48:49]
	v_cvt_pk_bf16_f32 v126, v122, v123
	v_cvt_pk_bf16_f32 v127, v124, v125
	v_mad_i64_i32 v[122:123], s[10:11], v137, s17, v[128:129]
	v_lshlrev_b64 v[124:125], 1, v[156:157]
	v_lshl_add_u64 v[122:123], v[122:123], 0, v[124:125]
	v_mov_b32_e32 v208, v126
	v_mov_b32_e32 v209, v127
	s_waitcnt lgkmcnt(1)
	v_cndmask_b32_e64 v185, v148, v186, s[40:41]
	v_mov_b32_e32 v126, v113
	v_mov_b32_e32 v127, v141
	s_waitcnt lgkmcnt(0)
	v_cndmask_b32_e64 v113, v191, v204, s[42:43]
	v_pk_mul_f32 v[126:127], v[126:127], v[184:185]
	v_fma_f32 v113, v117, v113, v121
	v_add_f32_e32 v113, v127, v113
	v_add_f32_e32 v126, v126, v113
	v_mul_f32_e32 v113, 0xbfb8aa3b, v126
	v_exp_f32_e32 v113, v113
	ds_bpermute_b32 v127, v161, v112
	ds_bpermute_b32 v186, v200, v112
	v_pk_mul_f32 v[110:111], v[110:111], v[136:137] op_sel_hi:[1,0]
	v_add_f32_e32 v113, 1.0, v113
	v_rcp_f32_e32 v179, v113
	s_waitcnt lgkmcnt(1)
	v_cndmask_b32_e64 v183, v127, v149, s[40:41]
	v_mov_b32_e32 v113, v140
	s_waitcnt lgkmcnt(0)
	v_cndmask_b32_e64 v149, v203, v186, s[42:43]
	v_pk_mul_f32 v[112:113], v[112:113], v[182:183]
	v_fma_f32 v149, v116, v149, v120
	v_add_f32_e32 v113, v113, v149
	v_add_f32_e32 v149, v112, v113
	ds_bpermute_b32 v137, v161, v110
	v_mul_f32_e32 v112, 0xbfb8aa3b, v149
	ds_bpermute_b32 v201, v161, v111
	ds_bpermute_b32 v202, v200, v111
	v_exp_f32_e32 v112, v112
	s_waitcnt lgkmcnt(2)
; __device__ __forceinline__ unsigned cvt_pk_bf16(float lo, float hi) { unsigned r; asm volatile("v_cvt_pk_bf16_f32 %0, %1, %2" : "=v"(r) : "v"(lo), "v"(hi)); return r; }
;     __device__ __forceinline__ void operator()(const f32x4 (&acc)[2][2][4][2], const Unit& u, int wr, int wc, int fr, int fq) const {
;     ...
;                 for (int m = 0; m < 4; ++m) {
;                     const f32x4 g = acc[ai][1][m][n] * rs[ai][m], v = acc[ai][0][m][n] * rs[ai][m];
;                     f32x4 r1, r2, a;
; #pragma unroll
;                     for (int e = 0; e < 4; ++e) { r1[e] = __shfl(g[e], src1); r2[e] = __shfl(g[e], src2); }
; #pragma unroll
;                     for (int e = 0; e < 4; ++e) {
;                         const float p1 = fr >= 1 ? r1[e] : r1p[e], p2 = fr >= 2 ? r2[e] : r2p[e];
;                         const float gg = b4[e] + w0[e] * p2 + w1[e] * p1 + w2[e] * g[e];
;                         a[e] = gg * __builtin_amdgcn_rcpf(1.f + __expf(-gg)) * v[e];
;                     }
;                     r1p = r1; r2p = r2;
;                     const size_t row = (size_t)(u.pm * BM + ai * HALF + wr * 64 + m * 16 + fr);
;                     if (m == 0 && fr < 2) {
;                         *(f32x4*)(GF + (size_t)(slab * 2 + fr) * FF + cbase) = g; *(f32x4*)(VF + (size_t)(slab * 2 + fr) * FF + cbase) = v;
;                     } else {
;                         typedef unsigned u32x2v __attribute__((ext_vector_type(2)));
;                         u32x2v w; w.x = cvt_pk_bf16(a[0], a[1]); w.y = cvt_pk_bf16(a[2], a[3]);
;                         *(u32x2v*)(ACT + row * FF + cbase) = w;
;                     }
;                     if (m == 3 && fr >= 14) *(f32x4*)(GL + (size_t)(slab * 2 + fr - 14) * FF + cbase) = g;
	v_pk_mul_f32 v[108:109], v[108:109], v[136:137] op_sel_hi:[1,0]
	v_mul_f32_e32 v113, v126, v179
	ds_bpermute_b32 v163, v200, v110
	v_add_f32_e32 v112, 1.0, v112
	v_mul_f32_e32 v109, v109, v113
	v_rcp_f32_e32 v126, v112
	s_waitcnt lgkmcnt(2)
	v_cndmask_b32_e64 v181, v201, v189, s[40:41]
	v_mov_b32_e32 v112, v111
	v_mov_b32_e32 v113, v139
	s_waitcnt lgkmcnt(1)
	v_cndmask_b32_e64 v111, v190, v202, s[42:43]
	v_pk_mul_f32 v[112:113], v[112:113], v[180:181]
	v_fma_f32 v111, v115, v111, v119
	v_add_f32_e32 v111, v113, v111
	v_add_f32_e32 v112, v112, v111
	v_mul_f32_e32 v111, 0xbfb8aa3b, v112
	v_exp_f32_e32 v113, v111
	v_cndmask_b32_e64 v179, v137, v143, s[40:41]
	v_mov_b32_e32 v111, v138
	s_waitcnt lgkmcnt(0)
	v_cndmask_b32_e64 v143, v187, v163, s[42:43]
	v_pk_mul_f32 v[110:111], v[110:111], v[178:179]
	v_fma_f32 v143, v114, v143, v118
	v_add_f32_e32 v111, v111, v143
	v_add_f32_e32 v110, v110, v111
	v_mul_f32_e32 v111, 0xbfb8aa3b, v110
	v_exp_f32_e32 v111, v111
	v_add_f32_e32 v113, 1.0, v113
	v_rcp_f32_e32 v113, v113
	v_fmamk_f32 v134, v134, 0x31000000, v232
	v_add_f32_e32 v111, 1.0, v111
	v_rcp_f32_e32 v111, v111
	v_rsq_f32_e32 v134, v134
	v_pk_mul_f32 v[106:107], v[106:107], v[136:137] op_sel_hi:[1,0]
	v_mul_f32_e32 v126, v149, v126
	v_mul_f32_e32 v112, v112, v113
	v_mul_f32_e32 v110, v110, v111
	v_or_b32_e32 v188, 32, v160
	v_mul_f32_e32 v108, v108, v126
	v_mul_f32_e32 v107, v107, v112
	v_mul_f32_e32 v106, v106, v110
	v_or_b32_e32 v135, 48, v160
	v_cvt_pk_bf16_f32 v106, v106, v107
	v_cvt_pk_bf16_f32 v107, v108, v109
	v_mad_i64_i32 v[108:109], s[10:11], v188, s17, v[128:129]
	v_lshl_add_u64 v[108:109], v[108:109], 0, v[124:125]
	v_pk_mul_f32 v[104:105], v[104:105], v[134:135] op_sel_hi:[1,0]
	v_mov_b32_e32 v210, v106
	v_mov_b32_e32 v211, v107
	ds_bpermute_b32 v106, v161, v105
	ds_bpermute_b32 v126, v200, v105
	v_mov_b32_e32 v107, v141
	ds_bpermute_b32 v143, v200, v104
	v_pk_mul_f32 v[102:103], v[102:103], v[134:135] op_sel_hi:[1,0]
	s_waitcnt lgkmcnt(2)
	v_cndmask_b32_e64 v185, v106, v148, s[40:41]
	v_mov_b32_e32 v106, v105
	s_waitcnt lgkmcnt(1)
	v_cndmask_b32_e64 v126, v204, v126, s[42:43]
	v_pk_mul_f32 v[106:107], v[106:107], v[184:185]
	v_fma_f32 v126, v117, v126, v121
	v_add_f32_e32 v107, v107, v126
	v_add_f32_e32 v126, v106, v107
	v_mul_f32_e32 v106, 0xbfb8aa3b, v126
	v_exp_f32_e32 v106, v106
	ds_bpermute_b32 v107, v161, v104
	ds_bpermute_b32 v112, v161, v103
	ds_bpermute_b32 v113, v200, v103
	v_add_f32_e32 v106, 1.0, v106
	v_rcp_f32_e32 v148, v106
	s_waitcnt lgkmcnt(2)
	v_cndmask_b32_e64 v183, v107, v127, s[40:41]
	v_mov_b32_e32 v106, v104
	v_mov_b32_e32 v107, v140
	v_cndmask_b32_e64 v127, v186, v143, s[42:43]
	v_pk_mul_f32 v[106:107], v[106:107], v[182:183]
	v_fma_f32 v127, v116, v127, v120
	v_add_f32_e32 v107, v107, v127
	v_add_f32_e32 v127, v106, v107
	v_mul_f32_e32 v106, 0xbfb8aa3b, v127
	v_exp_f32_e32 v106, v106
	v_pk_mul_f32 v[100:101], v[100:101], v[134:135] op_sel_hi:[1,0]
	v_mul_f32_e32 v107, v126, v148
	ds_bpermute_b32 v110, v161, v102
	v_add_f32_e32 v106, 1.0, v106
	ds_bpermute_b32 v111, v200, v102
	v_mul_f32_e32 v101, v101, v107
	v_rcp_f32_e32 v126, v106
	s_waitcnt lgkmcnt(3)
	v_cndmask_b32_e64 v181, v112, v201, s[40:41]
	v_mov_b32_e32 v106, v103
	v_mov_b32_e32 v107, v139
	s_waitcnt lgkmcnt(2)
	v_cndmask_b32_e64 v112, v202, v113, s[42:43]
	v_pk_mul_f32 v[106:107], v[106:107], v[180:181]
	v_fma_f32 v112, v115, v112, v119
	v_add_f32_e32 v107, v107, v112
	v_add_f32_e32 v112, v106, v107
	v_mul_f32_e32 v106, 0xbfb8aa3b, v112
	v_exp_f32_e32 v113, v106
	s_waitcnt lgkmcnt(1)
	v_cndmask_b32_e64 v179, v110, v137, s[40:41]
	v_mov_b32_e32 v106, v102
	v_mov_b32_e32 v107, v138
	s_waitcnt lgkmcnt(0)
	v_cndmask_b32_e64 v110, v163, v111, s[42:43]
	v_pk_mul_f32 v[106:107], v[106:107], v[178:179]
	v_fma_f32 v110, v114, v110, v118
	v_add_f32_e32 v107, v107, v110
	v_add_f32_e32 v106, v106, v107
	v_mul_f32_e32 v107, 0xbfb8aa3b, v106
	v_exp_f32_e32 v107, v107
	v_add_f32_e32 v111, 1.0, v113
	v_rcp_f32_e32 v111, v111
	v_mul_f32_e32 v110, v127, v126
	v_add_f32_e32 v107, 1.0, v107
	v_rcp_f32_e32 v107, v107
	v_pk_mul_f32 v[98:99], v[98:99], v[134:135] op_sel_hi:[1,0]
	v_mul_f32_e32 v100, v100, v110
	v_mul_f32_e32 v110, v112, v111
	v_mul_f32_e32 v106, v106, v107
	v_mul_f32_e32 v99, v99, v110
	v_mul_f32_e32 v98, v98, v106
	v_cvt_pk_bf16_f32 v98, v98, v99
	v_cvt_pk_bf16_f32 v99, v100, v101
	v_mad_i64_i32 v[100:101], s[10:11], v135, s17, v[128:129]
	v_readlane_b32 s10, v254, 44
	v_lshl_add_u64 v[110:111], v[100:101], 0, v[124:125]
	v_readlane_b32 s11, v254, 45
	v_mov_b32_e32 v212, v98
	v_mov_b32_e32 v213, v99
	s_nop 0
	v_lshl_add_u64 v[98:99], s[10:11], 0, v[146:147]
	v_lshl_add_u64 v[106:107], v[156:157], 2, v[98:99]
	s_and_saveexec_b64 s[10:11], s[44:45]
	v_readlane_b32 s85, v254, 57
	v_readlane_b32 s93, v254, 58
	s_cbranch_execz .LBB0_47
	global_store_dwordx4 v[106:107], v[102:105], off

; __device__ __forceinline__ unsigned cvt_pk_bf16(float lo, float hi) { unsigned r; asm volatile("v_cvt_pk_bf16_f32 %0, %1, %2" : "=v"(r) : "v"(lo), "v"(hi)); return r; }
;     __device__ __forceinline__ void operator()(const f32x4 (&acc)[2][2][4][2], const Unit& u, int wr, int wc, int fr, int fq) const {
;     ...
;                 for (int m = 0; m < 4; ++m) {
;                     const f32x4 g = acc[ai][1][m][n] * rs[ai][m], v = acc[ai][0][m][n] * rs[ai][m];
;                     f32x4 r1, r2, a;
; #pragma unroll
;                     for (int e = 0; e < 4; ++e) { r1[e] = __shfl(g[e], src1); r2[e] = __shfl(g[e], src2); }
; #pragma unroll
;                     for (int e = 0; e < 4; ++e) {
;                         const float p1 = fr >= 1 ? r1[e] : r1p[e], p2 = fr >= 2 ? r2[e] : r2p[e];
;                         const float gg = b4[e] + w0[e] * p2 + w1[e] * p1 + w2[e] * g[e];
;                         a[e] = gg * __builtin_amdgcn_rcpf(1.f + __expf(-gg)) * v[e];
;                     }
;                     r1p = r1; r2p = r2;
;                     const size_t row = (size_t)(u.pm * BM + ai * HALF + wr * 64 + m * 16 + fr);
;                     if (m == 0 && fr < 2) {
;                         *(f32x4*)(GF + (size_t)(slab * 2 + fr) * FF + cbase) = g; *(f32x4*)(VF + (size_t)(slab * 2 + fr) * FF + cbase) = v;
;                     } else {
;                         typedef unsigned u32x2v __attribute__((ext_vector_type(2)));
;                         u32x2v w; w.x = cvt_pk_bf16(a[0], a[1]); w.y = cvt_pk_bf16(a[2], a[3]);
;                         *(u32x2v*)(ACT + row * FF + cbase) = w;
.LBB0_51:
	s_or_b64 exec, exec, s[10:11]
	s_nop 0
	v_ffbh_u32_e32 v90, v175
	v_min_u32_e32 v93, 32, v90
	v_lshlrev_b64 v[90:91], v93, v[174:175]
	v_min_u32_e32 v90, 1, v90
	v_or_b32_e32 v90, v91, v90
	v_cvt_f32_u32_e32 v90, v90
	v_sub_u32_e32 v91, 32, v93
	v_add_u32_e32 v92, s12, v197
	s_movk_i32 s10, 0x5600
	v_ldexp_f32 v90, v90, v91
	v_mad_i64_i32 v[100:101], s[10:11], v92, s10, 0
	v_fmamk_f32 v92, v90, 0x31000000, v232
	v_rsq_f32_e32 v94, v92
	v_add_u32_e32 v95, 0x90, v160
	v_ffbh_u32_e32 v90, v173
	v_min_u32_e32 v93, 32, v90
	v_pk_mul_f32 v[88:89], v[88:89], v[94:95] op_sel_hi:[1,0]
	ds_bpermute_b32 v131, v161, v89
	ds_bpermute_b32 v138, v200, v89
	v_mov_b32_e32 v96, v89
	v_lshlrev_b64 v[90:91], v93, v[172:173]
	v_min_u32_e32 v90, 1, v90
	s_waitcnt lgkmcnt(1)
	v_cndmask_b32_e64 v97, v131, v179, s[40:41]
	s_waitcnt lgkmcnt(0)
	v_cndmask_b32_e64 v89, v181, v138, s[42:43]
	v_pk_mul_f32 v[96:97], v[126:127], v[96:97]
	v_fma_f32 v89, v117, v89, v121
	v_add_f32_e32 v89, v97, v89
	v_add_f32_e32 v96, v96, v89
	v_mul_f32_e32 v89, 0xbfb8aa3b, v96
	v_or_b32_e32 v90, v91, v90
	v_exp_f32_e32 v89, v89
	ds_bpermute_b32 v97, v161, v88
	ds_bpermute_b32 v140, v200, v88
	v_cvt_f32_u32_e32 v90, v90
	v_sub_u32_e32 v91, 32, v93
	v_add_f32_e32 v89, 1.0, v89
	v_rcp_f32_e32 v98, v89
	v_ldexp_f32 v90, v90, v91
	s_waitcnt lgkmcnt(1)
	v_cndmask_b32_e64 v89, v97, v163, s[40:41]
	s_waitcnt lgkmcnt(0)
	v_cndmask_b32_e64 v99, v143, v140, s[42:43]
	v_fmamk_f32 v92, v90, 0x31000000, v232
	v_ffbh_u32_e32 v90, v171
	v_pk_mul_f32 v[88:89], v[148:149], v[88:89]
	v_fma_f32 v99, v116, v99, v120
	v_min_u32_e32 v93, 32, v90
	v_add_f32_e32 v89, v89, v99
	v_lshlrev_b64 v[90:91], v93, v[170:171]
	v_add_f32_e32 v99, v88, v89
	v_min_u32_e32 v90, 1, v90
	v_pk_mul_f32 v[86:87], v[86:87], v[94:95] op_sel_hi:[1,0]
	v_mul_f32_e32 v88, 0xbfb8aa3b, v99
	v_or_b32_e32 v90, v91, v90
	ds_bpermute_b32 v133, v161, v87
	ds_bpermute_b32 v139, v200, v87
	v_exp_f32_e32 v88, v88
	v_cvt_f32_u32_e32 v90, v90
	v_sub_u32_e32 v93, 32, v93
	v_pk_mul_f32 v[84:85], v[84:85], v[94:95] op_sel_hi:[1,0]
	v_mul_f32_e32 v89, v96, v98
	v_add_f32_e32 v88, 1.0, v88
	v_ldexp_f32 v90, v90, v93
	ds_bpermute_b32 v93, v161, v86
	ds_bpermute_b32 v132, v200, v86
	v_mul_f32_e32 v85, v85, v89
	v_rcp_f32_e32 v96, v88
	s_waitcnt lgkmcnt(3)
	v_cndmask_b32_e64 v89, v133, v177, s[40:41]
	v_mov_b32_e32 v88, v87
	s_waitcnt lgkmcnt(2)
	v_cndmask_b32_e64 v87, v137, v139, s[42:43]
	v_pk_mul_f32 v[88:89], v[128:129], v[88:89]
	v_fma_f32 v87, v115, v87, v119
	v_add_f32_e32 v87, v89, v87
	v_add_f32_e32 v88, v88, v87
	v_mul_f32_e32 v87, 0xbfb8aa3b, v88
	v_exp_f32_e32 v89, v87
	s_waitcnt lgkmcnt(1)
	v_cndmask_b32_e64 v87, v93, v135, s[40:41]
	s_waitcnt lgkmcnt(0)
	v_cndmask_b32_e64 v98, v103, v132, s[42:43]
	v_pk_mul_f32 v[86:87], v[146:147], v[86:87]
	v_fma_f32 v98, v114, v98, v118
	v_add_f32_e32 v87, v87, v98
	v_add_f32_e32 v86, v86, v87
	v_mul_f32_e32 v87, 0xbfb8aa3b, v86
	v_exp_f32_e32 v87, v87
	v_add_f32_e32 v89, 1.0, v89
	v_rcp_f32_e32 v89, v89
	v_rsq_f32_e32 v92, v92
	v_add_f32_e32 v87, 1.0, v87
	v_rcp_f32_e32 v87, v87
	v_pk_mul_f32 v[82:83], v[82:83], v[94:95] op_sel_hi:[1,0]
	v_mul_f32_e32 v96, v99, v96
	v_mul_f32_e32 v88, v88, v89
	v_mul_f32_e32 v86, v86, v87
	v_mul_f32_e32 v84, v84, v96
	v_mul_f32_e32 v83, v83, v88
	v_mul_f32_e32 v82, v82, v86
	v_cvt_pk_bf16_f32 v82, v82, v83
	v_cvt_pk_bf16_f32 v83, v84, v85
	v_mov_b64_e32 v[84:85], s[48:49]
	v_mad_i64_i32 v[86:87], s[10:11], v95, s17, v[84:85]
	v_pk_mul_f32 v[80:81], v[80:81], v[92:93] op_sel_hi:[1,0]
	v_lshl_add_u64 v[98:99], v[86:87], 0, v[124:125]
	ds_bpermute_b32 v87, v161, v81
	ds_bpermute_b32 v95, v200, v81
	v_mov_b32_e32 v214, v82
	v_mov_b32_e32 v215, v83
	v_mov_b32_e32 v82, v81
	v_pk_mul_f32 v[78:79], v[78:79], v[92:93] op_sel_hi:[1,0]
	s_waitcnt lgkmcnt(1)
	v_cndmask_b32_e64 v83, v87, v131, s[40:41]
	s_waitcnt lgkmcnt(0)
	v_cndmask_b32_e64 v81, v138, v95, s[42:43]
	v_pk_mul_f32 v[82:83], v[126:127], v[82:83]
	v_fma_f32 v81, v117, v81, v121
	v_add_f32_e32 v81, v83, v81
	v_add_f32_e32 v82, v82, v81
	v_mul_f32_e32 v81, 0xbfb8aa3b, v82
	v_exp_f32_e32 v81, v81
	ds_bpermute_b32 v83, v161, v80
	ds_bpermute_b32 v131, v200, v80
	ds_bpermute_b32 v89, v161, v79
	v_add_f32_e32 v81, 1.0, v81
	v_rcp_f32_e32 v96, v81
	s_waitcnt lgkmcnt(2)
	v_cndmask_b32_e64 v81, v83, v97, s[40:41]
	s_waitcnt lgkmcnt(1)
;     __device__ __forceinline__ void operator()(const f32x4 (&acc)[2][2][4][2], const Unit& u, int wr, int wc, int fr, int fq) const {
;     ...
;             for (int m = 0; m < 4; ++m) rs[ai][m] = __builtin_amdgcn_rsqf((float)ss[u.pm * BM + ai * HALF + wr * 64 + m * 16 + fr] * (1.f / (2048.f * 262144.f)) + 1e-6f);
; #pragma unroll
;         for (int n = 0; n < 2; ++n) {
;             const int cbase = 128 * u.pn + 32 * wc + 16 * n + 4 * fq;
;             const f32x4 w0 = *(const f32x4*)(cw + cbase), w1 = *(const f32x4*)(cw + FF + cbase), w2 = *(const f32x4*)(cw + 2 * FF + cbase), b4 = *(const f32x4*)(cb + cbase);
; #pragma unroll
;             for (int ai = 0; ai < 2; ++ai) {
;                 const int slab = u.pm * 4 + 2 * ai + wr;
;                 f32x4 r1p = (f32x4){0.f, 0.f, 0.f, 0.f}, r2p = (f32x4){0.f, 0.f, 0.f, 0.f};
; #pragma unroll
;                 for (int m = 0; m < 4; ++m) {
;                     const f32x4 g = acc[ai][1][m][n] * rs[ai][m], v = acc[ai][0][m][n] * rs[ai][m];
;                     f32x4 r1, r2, a;
; #pragma unroll
;                     for (int e = 0; e < 4; ++e) { r1[e] = __shfl(g[e], src1); r2[e] = __shfl(g[e], src2); }
; #pragma unroll
;                     for (int e = 0; e < 4; ++e) {
;                         const float p1 = fr >= 1 ? r1[e] : r1p[e], p2 = fr >= 2 ? r2[e] : r2p[e];
;                         const float gg = b4[e] + w0[e] * p2 + w1[e] * p1 + w2[e] * g[e];
;                         a[e] = gg * __builtin_amdgcn_rcpf(1.f + __expf(-gg)) * v[e];
;                     }
;                     r1p = r1; r2p = r2;
;                     const size_t row = (size_t)(u.pm * BM + ai * HALF + wr * 64 + m * 16 + fr);
;                     if (m == 0 && fr < 2) {
;                         *(f32x4*)(GF + (size_t)(slab * 2 + fr) * FF + cbase) = g; *(f32x4*)(VF + (size_t)(slab * 2 + fr) * FF + cbase) = v;
;                     } else {
;                         typedef unsigned u32x2v __attribute__((ext_vector_type(2)));
;                         u32x2v w; w.x = cvt_pk_bf16(a[0], a[1]); w.y = cvt_pk_bf16(a[2], a[3]);
;                         *(u32x2v*)(ACT + row * FF + cbase) = w;
;                     }
;                     if (m == 3 && fr >= 14) *(f32x4*)(GL + (size_t)(slab * 2 + fr - 14) * FF + cbase) = g;
	v_cndmask_b32_e64 v97, v140, v131, s[42:43]
	v_pk_mul_f32 v[80:81], v[148:149], v[80:81]
	v_fma_f32 v97, v116, v97, v120
	v_add_f32_e32 v81, v81, v97
	v_add_f32_e32 v97, v80, v81
	v_mul_f32_e32 v80, 0xbfb8aa3b, v97
	ds_bpermute_b32 v103, v200, v79
	v_exp_f32_e32 v80, v80
	v_pk_mul_f32 v[76:77], v[76:77], v[92:93] op_sel_hi:[1,0]
	v_mul_f32_e32 v81, v82, v96
	ds_bpermute_b32 v86, v161, v78
	v_add_f32_e32 v80, 1.0, v80
	ds_bpermute_b32 v88, v200, v78
	v_mul_f32_e32 v77, v77, v81
	v_rcp_f32_e32 v82, v80
	s_waitcnt lgkmcnt(3)
	v_cndmask_b32_e64 v81, v89, v133, s[40:41]
	v_mov_b32_e32 v80, v79
	s_waitcnt lgkmcnt(2)
	v_cndmask_b32_e64 v79, v139, v103, s[42:43]
	v_pk_mul_f32 v[80:81], v[128:129], v[80:81]
	v_fma_f32 v79, v115, v79, v119
	v_add_f32_e32 v79, v81, v79
	v_add_f32_e32 v80, v80, v79
	v_mul_f32_e32 v79, 0xbfb8aa3b, v80
	v_pk_mul_f32 v[74:75], v[74:75], v[92:93] op_sel_hi:[1,0]
	v_exp_f32_e32 v81, v79
	s_waitcnt lgkmcnt(1)
	v_cndmask_b32_e64 v79, v86, v93, s[40:41]
	s_waitcnt lgkmcnt(0)
	v_cndmask_b32_e64 v93, v132, v88, s[42:43]
	v_pk_mul_f32 v[78:79], v[146:147], v[78:79]
	v_fma_f32 v93, v114, v93, v118
	v_add_f32_e32 v79, v79, v93
	v_add_f32_e32 v78, v78, v79
	v_mul_f32_e32 v79, 0xbfb8aa3b, v78
	v_exp_f32_e32 v79, v79
	v_add_f32_e32 v81, 1.0, v81
	v_rcp_f32_e32 v81, v81
	v_fmamk_f32 v90, v90, 0x31000000, v232
	v_add_f32_e32 v79, 1.0, v79
	v_rcp_f32_e32 v79, v79
	v_rsq_f32_e32 v90, v90
	v_mul_f32_e32 v82, v97, v82
	v_mul_f32_e32 v80, v80, v81
	v_mul_f32_e32 v78, v78, v79
	v_add_u32_e32 v130, 0xa0, v160
	v_mul_f32_e32 v76, v76, v82
	v_mul_f32_e32 v75, v75, v80
	v_mul_f32_e32 v74, v74, v78
	v_add_u32_e32 v91, 0xb0, v160
	v_cvt_pk_bf16_f32 v74, v74, v75
	v_cvt_pk_bf16_f32 v75, v76, v77
	v_mad_i64_i32 v[76:77], s[10:11], v130, s17, v[84:85]
	v_lshl_add_u64 v[96:97], v[76:77], 0, v[124:125]
	v_pk_mul_f32 v[72:73], v[72:73], v[90:91] op_sel_hi:[1,0]
	v_mov_b32_e32 v216, v74
	v_mov_b32_e32 v217, v75
	ds_bpermute_b32 v74, v161, v73
	ds_bpermute_b32 v79, v200, v73
	ds_bpermute_b32 v81, v200, v72
	v_pk_mul_f32 v[70:71], v[70:71], v[90:91] op_sel_hi:[1,0]
	ds_bpermute_b32 v78, v161, v71
	s_waitcnt lgkmcnt(3)
	v_cndmask_b32_e64 v75, v74, v87, s[40:41]
	v_mov_b32_e32 v74, v73
	s_waitcnt lgkmcnt(2)
	v_cndmask_b32_e64 v79, v95, v79, s[42:43]
	v_pk_mul_f32 v[74:75], v[126:127], v[74:75]
	v_fma_f32 v79, v117, v79, v121
	v_add_f32_e32 v75, v75, v79
	v_add_f32_e32 v79, v74, v75
	v_mul_f32_e32 v74, 0xbfb8aa3b, v79
	v_exp_f32_e32 v74, v74
	ds_bpermute_b32 v75, v161, v72
	s_waitcnt lgkmcnt(2)
	v_cndmask_b32_e64 v81, v131, v81, s[42:43]
	v_fma_f32 v81, v116, v81, v120
	v_add_f32_e32 v74, 1.0, v74
	v_rcp_f32_e32 v82, v74
	s_waitcnt lgkmcnt(0)
	v_cndmask_b32_e64 v75, v75, v83, s[40:41]
	v_mov_b32_e32 v74, v72
	v_pk_mul_f32 v[74:75], v[148:149], v[74:75]
	ds_bpermute_b32 v80, v200, v71
	v_add_f32_e32 v75, v75, v81
	v_add_f32_e32 v81, v74, v75
	v_mul_f32_e32 v74, 0xbfb8aa3b, v81
	v_exp_f32_e32 v74, v74
	v_pk_mul_f32 v[68:69], v[68:69], v[90:91] op_sel_hi:[1,0]
	v_mul_f32_e32 v75, v79, v82
	ds_bpermute_b32 v76, v161, v70
	v_add_f32_e32 v74, 1.0, v74
	ds_bpermute_b32 v77, v200, v70
	v_mul_f32_e32 v69, v69, v75
	v_rcp_f32_e32 v79, v74
	v_cndmask_b32_e64 v75, v78, v89, s[40:41]
	v_mov_b32_e32 v74, v71
	s_waitcnt lgkmcnt(2)
	v_cndmask_b32_e64 v78, v103, v80, s[42:43]
	v_pk_mul_f32 v[74:75], v[128:129], v[74:75]
	v_fma_f32 v78, v115, v78, v119
	v_add_f32_e32 v75, v75, v78
	v_add_f32_e32 v78, v74, v75
	v_mul_f32_e32 v74, 0xbfb8aa3b, v78
	v_exp_f32_e32 v80, v74
	s_waitcnt lgkmcnt(1)
	v_cndmask_b32_e64 v75, v76, v86, s[40:41]
	v_mov_b32_e32 v74, v70
	s_waitcnt lgkmcnt(0)
	v_cndmask_b32_e64 v76, v88, v77, s[42:43]
	v_pk_mul_f32 v[74:75], v[146:147], v[74:75]
	v_fmac_f32_e32 v118, v114, v76
	v_add_f32_e32 v75, v75, v118
	v_add_f32_e32 v74, v74, v75
	v_mul_f32_e32 v75, 0xbfb8aa3b, v74
	v_exp_f32_e32 v75, v75
	v_add_f32_e32 v77, 1.0, v80
	v_rcp_f32_e32 v77, v77
	v_mul_f32_e32 v76, v81, v79
	v_add_f32_e32 v75, 1.0, v75
	v_rcp_f32_e32 v75, v75
	v_pk_mul_f32 v[66:67], v[66:67], v[90:91] op_sel_hi:[1,0]
	v_mul_f32_e32 v68, v68, v76
	v_mul_f32_e32 v76, v78, v77
	v_mul_f32_e32 v74, v74, v75
	v_mul_f32_e32 v67, v67, v76
	v_mul_f32_e32 v66, v66, v74
	v_cvt_pk_bf16_f32 v66, v66, v67
	v_cvt_pk_bf16_f32 v67, v68, v69
	v_mad_i64_i32 v[68:69], s[10:11], v91, s17, v[84:85]
	v_readlane_b32 s10, v254, 44
	v_lshl_add_u64 v[88:89], v[68:69], 0, v[124:125]
	v_readlane_b32 s11, v254, 45
	v_mov_b32_e32 v218, v66
	v_mov_b32_e32 v219, v67
	s_nop 0
	v_lshl_add_u64 v[66:67], s[10:11], 0, v[100:101]
	v_lshl_add_u64 v[86:87], v[156:157], 2, v[66:67]
	s_and_saveexec_b64 s[10:11], s[44:45]
	s_cbranch_execz .LBB0_53
	global_store_dwordx4 v[86:87], v[70:73], off

; __device__ __forceinline__ unsigned cvt_pk_bf16(float lo, float hi) { unsigned r; asm volatile("v_cvt_pk_bf16_f32 %0, %1, %2" : "=v"(r) : "v"(lo), "v"(hi)); return r; }
;     __device__ __forceinline__ void operator()(const f32x4 (&acc)[2][2][4][2], const Unit& u, int wr, int wc, int fr, int fq) const {
;     ...
;                 for (int m = 0; m < 4; ++m) {
;                     const f32x4 g = acc[ai][1][m][n] * rs[ai][m], v = acc[ai][0][m][n] * rs[ai][m];
;                     f32x4 r1, r2, a;
; #pragma unroll
;                     for (int e = 0; e < 4; ++e) { r1[e] = __shfl(g[e], src1); r2[e] = __shfl(g[e], src2); }
; #pragma unroll
;                     for (int e = 0; e < 4; ++e) {
;                         const float p1 = fr >= 1 ? r1[e] : r1p[e], p2 = fr >= 2 ? r2[e] : r2p[e];
;                         const float gg = b4[e] + w0[e] * p2 + w1[e] * p1 + w2[e] * g[e];
;                         a[e] = gg * __builtin_amdgcn_rcpf(1.f + __expf(-gg)) * v[e];
;                     }
;                     r1p = r1; r2p = r2;
;                     const size_t row = (size_t)(u.pm * BM + ai * HALF + wr * 64 + m * 16 + fr);
;                     if (m == 0 && fr < 2) {
;                         *(f32x4*)(GF + (size_t)(slab * 2 + fr) * FF + cbase) = g; *(f32x4*)(VF + (size_t)(slab * 2 + fr) * FF + cbase) = v;
;                     } else {
;                         typedef unsigned u32x2v __attribute__((ext_vector_type(2)));
;                         u32x2v w; w.x = cvt_pk_bf16(a[0], a[1]); w.y = cvt_pk_bf16(a[2], a[3]);
;                         *(u32x2v*)(ACT + row * FF + cbase) = w;
;                     }
;                     if (m == 3 && fr >= 14) *(f32x4*)(GL + (size_t)(slab * 2 + fr - 14) * FF + cbase) = g;
.LBB0_57:
	s_or_b64 exec, exec, s[10:11]
	v_mov_b32_e32 v58, v142
	v_mov_b32_e32 v59, v142
	v_pk_mul_f32 v[56:57], v[56:57], v[58:59]
	ds_bpermute_b32 v83, v161, v57
	ds_bpermute_b32 v114, v200, v57
	v_mov_b32_e32 v60, v57
	s_waitcnt vmcnt(2)
	v_mov_b32_e32 v61, v81
	v_pk_mul_f32 v[52:53], v[52:53], v[58:59]
	s_waitcnt lgkmcnt(1)
	v_cndmask_b32_e64 v65, v83, v119, s[40:41]
	s_waitcnt lgkmcnt(0)
	v_cndmask_b32_e64 v57, v103, v114, s[42:43]
	v_pk_mul_f32 v[60:61], v[60:61], v[64:65]
	s_waitcnt vmcnt(0)
	v_fma_f32 v57, v69, v57, v73
	v_add_f32_e32 v57, v61, v57
	v_add_f32_e32 v60, v60, v57
	v_mul_f32_e32 v57, 0xbfb8aa3b, v60
	v_exp_f32_e32 v57, v57
	ds_bpermute_b32 v61, v161, v56
	ds_bpermute_b32 v103, v200, v56
	v_mov_b32_e32 v143, v142
	v_add_f32_e32 v57, 1.0, v57
	v_rcp_f32_e32 v58, v57
	s_waitcnt lgkmcnt(1)
	v_cndmask_b32_e64 v77, v61, v117, s[40:41]
	v_mov_b32_e32 v57, v80
	s_waitcnt lgkmcnt(0)
	v_cndmask_b32_e64 v59, v95, v103, s[42:43]
	v_pk_mul_f32 v[56:57], v[56:57], v[76:77]
	v_fma_f32 v59, v68, v59, v72
	v_add_f32_e32 v57, v57, v59
	v_add_f32_e32 v59, v56, v57
	v_pk_mul_f32 v[54:55], v[54:55], v[142:143]
	v_mul_f32_e32 v56, 0xbfb8aa3b, v59
	ds_bpermute_b32 v85, v161, v55
	ds_bpermute_b32 v100, v200, v55
	v_exp_f32_e32 v56, v56
	v_mul_f32_e32 v57, v60, v58
	ds_bpermute_b32 v82, v161, v54
	ds_bpermute_b32 v84, v200, v54
	v_add_f32_e32 v56, 1.0, v56
	v_mul_f32_e32 v53, v53, v57
	v_rcp_f32_e32 v58, v56
	s_waitcnt lgkmcnt(3)
	v_cndmask_b32_e64 v63, v85, v115, s[40:41]
	v_mov_b32_e32 v56, v55
	v_mov_b32_e32 v57, v79
	s_waitcnt lgkmcnt(2)
	v_cndmask_b32_e64 v55, v93, v100, s[42:43]
	v_pk_mul_f32 v[56:57], v[56:57], v[62:63]
	v_fma_f32 v55, v67, v55, v71
	v_add_f32_e32 v55, v57, v55
	v_add_f32_e32 v56, v56, v55
	v_mul_f32_e32 v55, 0xbfb8aa3b, v56
	v_exp_f32_e32 v57, v55
	s_waitcnt lgkmcnt(1)
	v_cndmask_b32_e64 v75, v82, v101, s[40:41]
	v_mov_b32_e32 v55, v78
	s_waitcnt lgkmcnt(0)
	v_cndmask_b32_e64 v60, v91, v84, s[42:43]
	v_pk_mul_f32 v[54:55], v[54:55], v[74:75]
	v_fma_f32 v60, v66, v60, v70
	v_add_f32_e32 v55, v55, v60
	v_add_f32_e32 v54, v54, v55
	v_mul_f32_e32 v55, 0xbfb8aa3b, v54
	v_exp_f32_e32 v55, v55
	v_add_f32_e32 v57, 1.0, v57
	v_rcp_f32_e32 v57, v57
	v_pk_mul_f32 v[50:51], v[50:51], v[142:143]
	v_add_f32_e32 v55, 1.0, v55
	v_rcp_f32_e32 v55, v55
	v_mul_f32_e32 v56, v56, v57
	v_mul_f32_e32 v58, v59, v58
	v_mul_f32_e32 v51, v51, v56
	v_mul_f32_e32 v54, v54, v55
	v_mul_f32_e32 v50, v50, v54
	v_mul_f32_e32 v52, v52, v58
	v_cvt_pk_bf16_f32 v50, v50, v51
	v_cvt_pk_bf16_f32 v51, v52, v53
	s_nop 1
	v_permlane16_swap_b32_e32 v208, v50
	v_permlane16_swap_b32_e32 v209, v51
	v_mov_b32_e32 v220, v208
	v_mov_b32_e32 v221, v209
	v_mov_b32_e32 v222, v50
	v_mov_b32_e32 v223, v51
	v_add_co_u32_e64 v206, s[98:99], v122, v205
	s_nop 1
	v_addc_co_u32_e64 v207, s[98:99], 0, v123, s[98:99]
	global_store_dwordx4 v[206:207], v[220:223], off
	v_mov_b32_e32 v50, v136
	v_mov_b32_e32 v51, v136
	v_pk_mul_f32 v[48:49], v[48:49], v[50:51]
	ds_bpermute_b32 v55, v161, v49
	ds_bpermute_b32 v59, v200, v49
	v_mov_b32_e32 v52, v49
	v_mov_b32_e32 v53, v81
	ds_bpermute_b32 v60, v200, v48
	s_waitcnt lgkmcnt(2)
	v_cndmask_b32_e64 v65, v55, v83, s[40:41]
	s_waitcnt lgkmcnt(1)
	v_cndmask_b32_e64 v49, v114, v59, s[42:43]
	v_pk_mul_f32 v[52:53], v[52:53], v[64:65]
	v_fma_f32 v49, v69, v49, v73
	v_add_f32_e32 v49, v53, v49
	v_add_f32_e32 v52, v52, v49
	v_mul_f32_e32 v49, 0xbfb8aa3b, v52
	v_exp_f32_e32 v49, v49
	ds_bpermute_b32 v53, v161, v48
	v_pk_mul_f32 v[44:45], v[44:45], v[50:51]
	s_waitcnt lgkmcnt(1)
	v_cndmask_b32_e64 v51, v103, v60, s[42:43]
	v_add_f32_e32 v49, 1.0, v49
	v_rcp_f32_e32 v50, v49
	s_waitcnt lgkmcnt(0)
	v_cndmask_b32_e64 v77, v53, v61, s[40:41]
	v_mov_b32_e32 v49, v80
	v_pk_mul_f32 v[48:49], v[48:49], v[76:77]
	v_fma_f32 v51, v68, v51, v72
	v_add_f32_e32 v49, v49, v51
	v_mov_b32_e32 v137, v136
	v_add_f32_e32 v51, v48, v49
	v_pk_mul_f32 v[46:47], v[46:47], v[136:137]
	v_mul_f32_e32 v48, 0xbfb8aa3b, v51
	ds_bpermute_b32 v57, v161, v47
	ds_bpermute_b32 v58, v200, v47
	v_exp_f32_e32 v48, v48
	v_mul_f32_e32 v49, v52, v50
	ds_bpermute_b32 v54, v161, v46
	ds_bpermute_b32 v56, v200, v46
	v_add_f32_e32 v48, 1.0, v48
	v_mul_f32_e32 v45, v45, v49
	v_rcp_f32_e32 v50, v48
	s_waitcnt lgkmcnt(3)
	v_cndmask_b32_e64 v63, v57, v85, s[40:41]
	v_mov_b32_e32 v48, v47
	v_mov_b32_e32 v49, v79
	s_waitcnt lgkmcnt(2)
; __device__ __forceinline__ unsigned cvt_pk_bf16(float lo, float hi) { unsigned r; asm volatile("v_cvt_pk_bf16_f32 %0, %1, %2" : "=v"(r) : "v"(lo), "v"(hi)); return r; }
;     __device__ __forceinline__ void operator()(const f32x4 (&acc)[2][2][4][2], const Unit& u, int wr, int wc, int fr, int fq) const {
;     ...
;                 for (int m = 0; m < 4; ++m) {
;                     const f32x4 g = acc[ai][1][m][n] * rs[ai][m], v = acc[ai][0][m][n] * rs[ai][m];
;                     f32x4 r1, r2, a;
; #pragma unroll
;                     for (int e = 0; e < 4; ++e) { r1[e] = __shfl(g[e], src1); r2[e] = __shfl(g[e], src2); }
; #pragma unroll
;                     for (int e = 0; e < 4; ++e) {
;                         const float p1 = fr >= 1 ? r1[e] : r1p[e], p2 = fr >= 2 ? r2[e] : r2p[e];
;                         const float gg = b4[e] + w0[e] * p2 + w1[e] * p1 + w2[e] * g[e];
;                         a[e] = gg * __builtin_amdgcn_rcpf(1.f + __expf(-gg)) * v[e];
;                     }
;                     r1p = r1; r2p = r2;
;                     const size_t row = (size_t)(u.pm * BM + ai * HALF + wr * 64 + m * 16 + fr);
;                     if (m == 0 && fr < 2) {
;                         *(f32x4*)(GF + (size_t)(slab * 2 + fr) * FF + cbase) = g; *(f32x4*)(VF + (size_t)(slab * 2 + fr) * FF + cbase) = v;
;                     } else {
;                         typedef unsigned u32x2v __attribute__((ext_vector_type(2)));
;                         u32x2v w; w.x = cvt_pk_bf16(a[0], a[1]); w.y = cvt_pk_bf16(a[2], a[3]);
;                         *(u32x2v*)(ACT + row * FF + cbase) = w;
;                     }
;                     if (m == 3 && fr >= 14) *(f32x4*)(GL + (size_t)(slab * 2 + fr - 14) * FF + cbase) = g;
	v_cndmask_b32_e64 v47, v100, v58, s[42:43]
	v_pk_mul_f32 v[48:49], v[48:49], v[62:63]
	v_fma_f32 v47, v67, v47, v71
	v_add_f32_e32 v47, v49, v47
	v_add_f32_e32 v48, v48, v47
	v_mul_f32_e32 v47, 0xbfb8aa3b, v48
	v_exp_f32_e32 v49, v47
	s_waitcnt lgkmcnt(1)
	v_cndmask_b32_e64 v75, v54, v82, s[40:41]
	v_mov_b32_e32 v47, v78
	s_waitcnt lgkmcnt(0)
	v_cndmask_b32_e64 v52, v84, v56, s[42:43]
	v_pk_mul_f32 v[46:47], v[46:47], v[74:75]
	v_fma_f32 v52, v66, v52, v70
	v_add_f32_e32 v47, v47, v52
	v_add_f32_e32 v46, v46, v47
	v_mul_f32_e32 v47, 0xbfb8aa3b, v46
	v_exp_f32_e32 v47, v47
	v_add_f32_e32 v49, 1.0, v49
	v_rcp_f32_e32 v49, v49
	v_pk_mul_f32 v[42:43], v[42:43], v[136:137]
	v_add_f32_e32 v47, 1.0, v47
	v_rcp_f32_e32 v47, v47
	v_mul_f32_e32 v48, v48, v49
	v_mul_f32_e32 v50, v51, v50
	v_mul_f32_e32 v43, v43, v48
	v_mul_f32_e32 v46, v46, v47
	v_mul_f32_e32 v42, v42, v46
	v_mul_f32_e32 v44, v44, v50
	v_cvt_pk_bf16_f32 v42, v42, v43
	v_cvt_pk_bf16_f32 v43, v44, v45
	s_nop 1
	v_permlane16_swap_b32_e32 v210, v42
	v_permlane16_swap_b32_e32 v211, v43
	v_mov_b32_e32 v220, v210
	v_mov_b32_e32 v221, v211
	v_mov_b32_e32 v222, v42
	v_mov_b32_e32 v223, v43
	v_add_co_u32_e64 v206, s[98:99], v108, v205
	s_nop 1
	v_addc_co_u32_e64 v207, s[98:99], 0, v109, s[98:99]
	global_store_dwordx4 v[206:207], v[220:223], off
	v_mov_b32_e32 v42, v134
	v_mov_b32_e32 v43, v134
	v_pk_mul_f32 v[40:41], v[40:41], v[42:43]
	ds_bpermute_b32 v44, v161, v41
	ds_bpermute_b32 v50, v200, v41
	v_mov_b32_e32 v45, v81
	ds_bpermute_b32 v51, v200, v40
	v_pk_mul_f32 v[36:37], v[36:37], v[42:43]
	s_waitcnt lgkmcnt(2)
	v_cndmask_b32_e64 v65, v44, v55, s[40:41]
	v_mov_b32_e32 v44, v41
	s_waitcnt lgkmcnt(1)
	v_cndmask_b32_e64 v50, v59, v50, s[42:43]
	v_pk_mul_f32 v[44:45], v[44:45], v[64:65]
	v_fma_f32 v50, v69, v50, v73
	v_add_f32_e32 v45, v45, v50
	v_add_f32_e32 v44, v44, v45
	v_mul_f32_e32 v45, 0xbfb8aa3b, v44
	v_exp_f32_e32 v45, v45
	ds_bpermute_b32 v50, v161, v40
	v_mov_b32_e32 v43, v80
	v_mov_b32_e32 v135, v134
	v_add_f32_e32 v42, 1.0, v45
	v_rcp_f32_e32 v45, v42
	s_waitcnt lgkmcnt(0)
	v_cndmask_b32_e64 v77, v50, v53, s[40:41]
	v_mov_b32_e32 v42, v40
	v_cndmask_b32_e64 v50, v60, v51, s[42:43]
	v_pk_mul_f32 v[42:43], v[42:43], v[76:77]
	v_fma_f32 v50, v68, v50, v72
	v_add_f32_e32 v43, v43, v50
	v_add_f32_e32 v50, v42, v43
	v_pk_mul_f32 v[38:39], v[38:39], v[134:135]
	v_mul_f32_e32 v42, 0xbfb8aa3b, v50
	ds_bpermute_b32 v48, v161, v39
	ds_bpermute_b32 v49, v200, v39
	v_exp_f32_e32 v42, v42
	v_mul_f32_e32 v43, v44, v45
	ds_bpermute_b32 v46, v161, v38
	ds_bpermute_b32 v47, v200, v38
	v_add_f32_e32 v42, 1.0, v42
	v_mul_f32_e32 v37, v37, v43
	v_rcp_f32_e32 v44, v42
	s_waitcnt lgkmcnt(3)
	v_cndmask_b32_e64 v63, v48, v57, s[40:41]
	v_mov_b32_e32 v42, v39
	v_mov_b32_e32 v43, v79
	s_waitcnt lgkmcnt(2)
	v_cndmask_b32_e64 v45, v58, v49, s[42:43]
	v_pk_mul_f32 v[42:43], v[42:43], v[62:63]
	v_fma_f32 v45, v67, v45, v71
	v_add_f32_e32 v43, v43, v45
	v_add_f32_e32 v45, v42, v43
	v_mul_f32_e32 v42, 0xbfb8aa3b, v45
	v_exp_f32_e32 v48, v42
	s_waitcnt lgkmcnt(1)
	v_cndmask_b32_e64 v75, v46, v54, s[40:41]
	v_mov_b32_e32 v42, v38
	v_mov_b32_e32 v43, v78
	s_waitcnt lgkmcnt(0)
	v_cndmask_b32_e64 v46, v56, v47, s[42:43]
	v_pk_mul_f32 v[42:43], v[42:43], v[74:75]
	v_fma_f32 v46, v66, v46, v70
	v_add_f32_e32 v43, v43, v46
	v_add_f32_e32 v42, v42, v43
	v_mul_f32_e32 v43, 0xbfb8aa3b, v42
	v_exp_f32_e32 v43, v43
	v_add_f32_e32 v46, 1.0, v48
	v_rcp_f32_e32 v46, v46
	v_mul_f32_e32 v44, v50, v44
	v_add_f32_e32 v43, 1.0, v43
	v_rcp_f32_e32 v43, v43
	v_pk_mul_f32 v[34:35], v[34:35], v[134:135]
	v_mul_f32_e32 v36, v36, v44
	v_mul_f32_e32 v44, v45, v46
	v_mul_f32_e32 v42, v42, v43
	v_mul_f32_e32 v35, v35, v44
	v_mul_f32_e32 v34, v34, v42
	v_cvt_pk_bf16_f32 v34, v34, v35
	v_cvt_pk_bf16_f32 v35, v36, v37
	s_nop 1
	v_permlane16_swap_b32_e32 v212, v34
	v_permlane16_swap_b32_e32 v213, v35
	v_mov_b32_e32 v220, v212
	v_mov_b32_e32 v221, v213
	v_mov_b32_e32 v222, v34
	v_mov_b32_e32 v223, v35
	v_add_co_u32_e64 v206, s[98:99], v110, v205
	s_nop 1
	v_addc_co_u32_e64 v207, s[98:99], 0, v111, s[98:99]
	global_store_dwordx4 v[206:207], v[220:223], off
	s_and_saveexec_b64 s[10:11], s[44:45]
	s_cbranch_execz .LBB0_59
	global_store_dwordx4 v[106:107], v[38:41], off offset:64

; __device__ __forceinline__ unsigned cvt_pk_bf16(float lo, float hi) { unsigned r; asm volatile("v_cvt_pk_bf16_f32 %0, %1, %2" : "=v"(r) : "v"(lo), "v"(hi)); return r; }
;     __device__ __forceinline__ void operator()(const f32x4 (&acc)[2][2][4][2], const Unit& u, int wr, int wc, int fr, int fq) const {
;     ...
;                 for (int m = 0; m < 4; ++m) {
;                     const f32x4 g = acc[ai][1][m][n] * rs[ai][m], v = acc[ai][0][m][n] * rs[ai][m];
;                     f32x4 r1, r2, a;
; #pragma unroll
;                     for (int e = 0; e < 4; ++e) { r1[e] = __shfl(g[e], src1); r2[e] = __shfl(g[e], src2); }
; #pragma unroll
;                     for (int e = 0; e < 4; ++e) {
;                         const float p1 = fr >= 1 ? r1[e] : r1p[e], p2 = fr >= 2 ? r2[e] : r2p[e];
;                         const float gg = b4[e] + w0[e] * p2 + w1[e] * p1 + w2[e] * g[e];
;                         a[e] = gg * __builtin_amdgcn_rcpf(1.f + __expf(-gg)) * v[e];
;                     }
;                     r1p = r1; r2p = r2;
;                     const size_t row = (size_t)(u.pm * BM + ai * HALF + wr * 64 + m * 16 + fr);
;                     if (m == 0 && fr < 2) {
;                         *(f32x4*)(GF + (size_t)(slab * 2 + fr) * FF + cbase) = g; *(f32x4*)(VF + (size_t)(slab * 2 + fr) * FF + cbase) = v;
;                     } else {
;                         typedef unsigned u32x2v __attribute__((ext_vector_type(2)));
;                         u32x2v w; w.x = cvt_pk_bf16(a[0], a[1]); w.y = cvt_pk_bf16(a[2], a[3]);
;                         *(u32x2v*)(ACT + row * FF + cbase) = w;
;                     }
;                     if (m == 3 && fr >= 14) *(f32x4*)(GL + (size_t)(slab * 2 + fr - 14) * FF + cbase) = g;
.LBB0_63:
	s_or_b64 exec, exec, s[10:11]
	s_nop 0
	v_mov_b32_e32 v26, v94
	v_mov_b32_e32 v27, v94
	v_pk_mul_f32 v[24:25], v[24:25], v[26:27]
	ds_bpermute_b32 v31, v161, v25
	ds_bpermute_b32 v35, v200, v25
	v_mov_b32_e32 v28, v25
	v_mov_b32_e32 v29, v81
	ds_bpermute_b32 v36, v200, v24
	s_waitcnt lgkmcnt(2)
	v_cndmask_b32_e64 v65, v31, v65, s[40:41]
	s_waitcnt lgkmcnt(1)
	v_cndmask_b32_e64 v25, v41, v35, s[42:43]
	v_pk_mul_f32 v[28:29], v[28:29], v[64:65]
	v_fma_f32 v25, v69, v25, v73
	v_add_f32_e32 v25, v29, v25
	v_add_f32_e32 v28, v28, v25
	v_mul_f32_e32 v25, 0xbfb8aa3b, v28
	v_exp_f32_e32 v25, v25
	ds_bpermute_b32 v29, v161, v24
	v_pk_mul_f32 v[20:21], v[20:21], v[26:27]
	s_waitcnt lgkmcnt(1)
	v_cndmask_b32_e64 v27, v40, v36, s[42:43]
	v_add_f32_e32 v25, 1.0, v25
	v_rcp_f32_e32 v26, v25
	s_waitcnt lgkmcnt(0)
	v_cndmask_b32_e64 v77, v29, v77, s[40:41]
	v_mov_b32_e32 v25, v80
	v_pk_mul_f32 v[24:25], v[24:25], v[76:77]
	v_fma_f32 v27, v68, v27, v72
	v_add_f32_e32 v25, v25, v27
	v_mov_b32_e32 v95, v94
	v_add_f32_e32 v27, v24, v25
	v_pk_mul_f32 v[22:23], v[22:23], v[94:95]
	v_mul_f32_e32 v24, 0xbfb8aa3b, v27
	ds_bpermute_b32 v33, v161, v23
	ds_bpermute_b32 v34, v200, v23
	v_exp_f32_e32 v24, v24
	v_mul_f32_e32 v25, v28, v26
	ds_bpermute_b32 v30, v161, v22
	ds_bpermute_b32 v32, v200, v22
	v_add_f32_e32 v24, 1.0, v24
	v_mul_f32_e32 v21, v21, v25
	v_rcp_f32_e32 v26, v24
	s_waitcnt lgkmcnt(3)
	v_cndmask_b32_e64 v63, v33, v63, s[40:41]
	v_mov_b32_e32 v24, v23
	v_mov_b32_e32 v25, v79
	s_waitcnt lgkmcnt(2)
	v_cndmask_b32_e64 v23, v39, v34, s[42:43]
	v_pk_mul_f32 v[24:25], v[24:25], v[62:63]
	v_fma_f32 v23, v67, v23, v71
	v_add_f32_e32 v23, v25, v23
	v_add_f32_e32 v24, v24, v23
	v_mul_f32_e32 v23, 0xbfb8aa3b, v24
	v_exp_f32_e32 v25, v23
	s_waitcnt lgkmcnt(1)
	v_cndmask_b32_e64 v75, v30, v75, s[40:41]
	v_mov_b32_e32 v23, v78
	s_waitcnt lgkmcnt(0)
	v_cndmask_b32_e64 v28, v38, v32, s[42:43]
	v_pk_mul_f32 v[22:23], v[22:23], v[74:75]
	v_fma_f32 v28, v66, v28, v70
	v_add_f32_e32 v23, v23, v28
	v_add_f32_e32 v22, v22, v23
	v_mul_f32_e32 v23, 0xbfb8aa3b, v22
	v_exp_f32_e32 v23, v23
	v_add_f32_e32 v25, 1.0, v25
	v_rcp_f32_e32 v25, v25
	v_pk_mul_f32 v[18:19], v[18:19], v[94:95]
	v_add_f32_e32 v23, 1.0, v23
	v_rcp_f32_e32 v23, v23
	v_mul_f32_e32 v24, v24, v25
	v_mul_f32_e32 v26, v27, v26
	v_mul_f32_e32 v19, v19, v24
	v_mul_f32_e32 v22, v22, v23
	v_mul_f32_e32 v18, v18, v22
	v_mul_f32_e32 v20, v20, v26
	v_cvt_pk_bf16_f32 v18, v18, v19
	v_cvt_pk_bf16_f32 v19, v20, v21
	s_nop 1
	v_permlane16_swap_b32_e32 v214, v18
	v_permlane16_swap_b32_e32 v215, v19
	v_mov_b32_e32 v220, v214
	v_mov_b32_e32 v221, v215
	v_mov_b32_e32 v222, v18
	v_mov_b32_e32 v223, v19
	v_add_co_u32_e64 v206, s[98:99], v98, v205
	s_nop 1
	v_addc_co_u32_e64 v207, s[98:99], 0, v99, s[98:99]
	global_store_dwordx4 v[206:207], v[220:223], off
	v_mov_b32_e32 v18, v92
	v_mov_b32_e32 v19, v92
	v_pk_mul_f32 v[16:17], v[16:17], v[18:19]
	ds_bpermute_b32 v23, v161, v17
	ds_bpermute_b32 v27, v200, v17
	v_mov_b32_e32 v20, v17
	v_mov_b32_e32 v21, v81
	ds_bpermute_b32 v28, v200, v16
	s_waitcnt lgkmcnt(2)
	v_cndmask_b32_e64 v65, v23, v31, s[40:41]
	s_waitcnt lgkmcnt(1)
	v_cndmask_b32_e64 v17, v35, v27, s[42:43]
	v_pk_mul_f32 v[20:21], v[20:21], v[64:65]
	v_fma_f32 v17, v69, v17, v73
	v_add_f32_e32 v17, v21, v17
	v_add_f32_e32 v20, v20, v17
	v_mul_f32_e32 v17, 0xbfb8aa3b, v20
	v_exp_f32_e32 v17, v17
	ds_bpermute_b32 v21, v161, v16
	v_pk_mul_f32 v[12:13], v[12:13], v[18:19]
	s_waitcnt lgkmcnt(1)
	v_cndmask_b32_e64 v19, v36, v28, s[42:43]
	v_add_f32_e32 v17, 1.0, v17
	v_rcp_f32_e32 v18, v17
	s_waitcnt lgkmcnt(0)
	v_cndmask_b32_e64 v77, v21, v29, s[40:41]
	v_mov_b32_e32 v17, v80
	v_pk_mul_f32 v[16:17], v[16:17], v[76:77]
	v_fma_f32 v19, v68, v19, v72
	v_add_f32_e32 v17, v17, v19
	v_mov_b32_e32 v93, v92
	v_add_f32_e32 v19, v16, v17
	v_pk_mul_f32 v[14:15], v[14:15], v[92:93]
	v_mul_f32_e32 v16, 0xbfb8aa3b, v19
	ds_bpermute_b32 v25, v161, v15
	ds_bpermute_b32 v26, v200, v15
	v_exp_f32_e32 v16, v16
	v_mul_f32_e32 v17, v20, v18
	ds_bpermute_b32 v22, v161, v14
	ds_bpermute_b32 v24, v200, v14
	v_add_f32_e32 v16, 1.0, v16
	v_mul_f32_e32 v13, v13, v17
	v_rcp_f32_e32 v18, v16
	s_waitcnt lgkmcnt(3)
; __device__ __forceinline__ unsigned cvt_pk_bf16(float lo, float hi) { unsigned r; asm volatile("v_cvt_pk_bf16_f32 %0, %1, %2" : "=v"(r) : "v"(lo), "v"(hi)); return r; }
;     __device__ __forceinline__ void operator()(const f32x4 (&acc)[2][2][4][2], const Unit& u, int wr, int wc, int fr, int fq) const {
;     ...
;                 for (int m = 0; m < 4; ++m) {
;                     const f32x4 g = acc[ai][1][m][n] * rs[ai][m], v = acc[ai][0][m][n] * rs[ai][m];
;                     f32x4 r1, r2, a;
; #pragma unroll
;                     for (int e = 0; e < 4; ++e) { r1[e] = __shfl(g[e], src1); r2[e] = __shfl(g[e], src2); }
; #pragma unroll
;                     for (int e = 0; e < 4; ++e) {
;                         const float p1 = fr >= 1 ? r1[e] : r1p[e], p2 = fr >= 2 ? r2[e] : r2p[e];
;                         const float gg = b4[e] + w0[e] * p2 + w1[e] * p1 + w2[e] * g[e];
;                         a[e] = gg * __builtin_amdgcn_rcpf(1.f + __expf(-gg)) * v[e];
;                     }
;                     r1p = r1; r2p = r2;
;                     const size_t row = (size_t)(u.pm * BM + ai * HALF + wr * 64 + m * 16 + fr);
;                     if (m == 0 && fr < 2) {
;                         *(f32x4*)(GF + (size_t)(slab * 2 + fr) * FF + cbase) = g; *(f32x4*)(VF + (size_t)(slab * 2 + fr) * FF + cbase) = v;
;                     } else {
;                         typedef unsigned u32x2v __attribute__((ext_vector_type(2)));
;                         u32x2v w; w.x = cvt_pk_bf16(a[0], a[1]); w.y = cvt_pk_bf16(a[2], a[3]);
;                         *(u32x2v*)(ACT + row * FF + cbase) = w;
;                     }
;                     if (m == 3 && fr >= 14) *(f32x4*)(GL + (size_t)(slab * 2 + fr - 14) * FF + cbase) = g;
	v_cndmask_b32_e64 v63, v25, v33, s[40:41]
	v_mov_b32_e32 v16, v15
	v_mov_b32_e32 v17, v79
	s_waitcnt lgkmcnt(2)
	v_cndmask_b32_e64 v15, v34, v26, s[42:43]
	v_pk_mul_f32 v[16:17], v[16:17], v[62:63]
	v_fma_f32 v15, v67, v15, v71
	v_add_f32_e32 v15, v17, v15
	v_add_f32_e32 v16, v16, v15
	v_mul_f32_e32 v15, 0xbfb8aa3b, v16
	v_exp_f32_e32 v17, v15
	s_waitcnt lgkmcnt(1)
	v_cndmask_b32_e64 v75, v22, v30, s[40:41]
	v_mov_b32_e32 v15, v78
	s_waitcnt lgkmcnt(0)
	v_cndmask_b32_e64 v20, v32, v24, s[42:43]
	v_pk_mul_f32 v[14:15], v[14:15], v[74:75]
	v_fma_f32 v20, v66, v20, v70
	v_add_f32_e32 v15, v15, v20
	v_add_f32_e32 v14, v14, v15
	v_mul_f32_e32 v15, 0xbfb8aa3b, v14
	v_exp_f32_e32 v15, v15
	v_add_f32_e32 v17, 1.0, v17
	v_rcp_f32_e32 v17, v17
	v_pk_mul_f32 v[10:11], v[10:11], v[92:93]
	v_add_f32_e32 v15, 1.0, v15
	v_rcp_f32_e32 v15, v15
	v_mul_f32_e32 v16, v16, v17
	v_mul_f32_e32 v18, v19, v18
	v_mul_f32_e32 v11, v11, v16
	v_mul_f32_e32 v14, v14, v15
	v_mul_f32_e32 v10, v10, v14
	v_mul_f32_e32 v12, v12, v18
	v_cvt_pk_bf16_f32 v10, v10, v11
	v_cvt_pk_bf16_f32 v11, v12, v13
	s_nop 1
	v_permlane16_swap_b32_e32 v216, v10
	v_permlane16_swap_b32_e32 v217, v11
	v_mov_b32_e32 v220, v216
	v_mov_b32_e32 v221, v217
	v_mov_b32_e32 v222, v10
	v_mov_b32_e32 v223, v11
	v_add_co_u32_e64 v206, s[98:99], v96, v205
	s_nop 1
	v_addc_co_u32_e64 v207, s[98:99], 0, v97, s[98:99]
	global_store_dwordx4 v[206:207], v[220:223], off
	v_mov_b32_e32 v10, v90
	v_mov_b32_e32 v11, v90
	v_pk_mul_f32 v[8:9], v[8:9], v[10:11]
	ds_bpermute_b32 v12, v161, v9
	ds_bpermute_b32 v18, v200, v9
	v_mov_b32_e32 v13, v81
	ds_bpermute_b32 v19, v200, v8
	v_pk_mul_f32 v[4:5], v[4:5], v[10:11]
	s_waitcnt lgkmcnt(2)
	v_cndmask_b32_e64 v65, v12, v23, s[40:41]
	v_mov_b32_e32 v12, v9
	s_waitcnt lgkmcnt(1)
	v_cndmask_b32_e64 v18, v27, v18, s[42:43]
	v_pk_mul_f32 v[12:13], v[12:13], v[64:65]
	v_fma_f32 v18, v69, v18, v73
	v_add_f32_e32 v13, v13, v18
	v_add_f32_e32 v12, v12, v13
	v_mul_f32_e32 v13, 0xbfb8aa3b, v12
	v_exp_f32_e32 v13, v13
	ds_bpermute_b32 v18, v161, v8
	v_mov_b32_e32 v11, v80
	v_mov_b32_e32 v91, v90
	v_add_f32_e32 v10, 1.0, v13
	v_rcp_f32_e32 v13, v10
	s_waitcnt lgkmcnt(0)
	v_cndmask_b32_e64 v77, v18, v21, s[40:41]
	v_mov_b32_e32 v10, v8
	v_cndmask_b32_e64 v18, v28, v19, s[42:43]
	v_pk_mul_f32 v[10:11], v[10:11], v[76:77]
	v_fma_f32 v18, v68, v18, v72
	v_add_f32_e32 v11, v11, v18
	v_add_f32_e32 v18, v10, v11
	v_pk_mul_f32 v[6:7], v[6:7], v[90:91]
	v_mul_f32_e32 v10, 0xbfb8aa3b, v18
	ds_bpermute_b32 v16, v161, v7
	ds_bpermute_b32 v17, v200, v7
	v_exp_f32_e32 v10, v10
	v_mul_f32_e32 v11, v12, v13
	ds_bpermute_b32 v14, v161, v6
	ds_bpermute_b32 v15, v200, v6
	v_add_f32_e32 v10, 1.0, v10
	v_mul_f32_e32 v5, v5, v11
	v_rcp_f32_e32 v12, v10
	s_waitcnt lgkmcnt(3)
	v_cndmask_b32_e64 v63, v16, v25, s[40:41]
	v_mov_b32_e32 v10, v7
	v_mov_b32_e32 v11, v79
	s_waitcnt lgkmcnt(2)
	v_cndmask_b32_e64 v13, v26, v17, s[42:43]
	v_pk_mul_f32 v[10:11], v[10:11], v[62:63]
	v_fma_f32 v13, v67, v13, v71
	v_add_f32_e32 v11, v11, v13
	v_add_f32_e32 v13, v10, v11
	v_mul_f32_e32 v10, 0xbfb8aa3b, v13
	v_exp_f32_e32 v16, v10
	s_waitcnt lgkmcnt(1)
	v_cndmask_b32_e64 v75, v14, v22, s[40:41]
	v_mov_b32_e32 v10, v6
	v_mov_b32_e32 v11, v78
	s_waitcnt lgkmcnt(0)
	v_cndmask_b32_e64 v14, v24, v15, s[42:43]
	v_pk_mul_f32 v[10:11], v[10:11], v[74:75]
	v_fmac_f32_e32 v70, v66, v14
	v_add_f32_e32 v11, v11, v70
	v_add_f32_e32 v10, v10, v11
	v_mul_f32_e32 v11, 0xbfb8aa3b, v10
	v_exp_f32_e32 v11, v11
	v_add_f32_e32 v14, 1.0, v16
	v_rcp_f32_e32 v14, v14
	v_mul_f32_e32 v12, v18, v12
	v_add_f32_e32 v11, 1.0, v11
	v_rcp_f32_e32 v11, v11
	v_pk_mul_f32 v[2:3], v[2:3], v[90:91]
	v_mul_f32_e32 v4, v4, v12
	v_mul_f32_e32 v12, v13, v14
	v_mul_f32_e32 v10, v10, v11
	v_mul_f32_e32 v3, v3, v12
	v_mul_f32_e32 v2, v2, v10
	v_cvt_pk_bf16_f32 v2, v2, v3
	v_cvt_pk_bf16_f32 v3, v4, v5
	s_nop 1
	v_permlane16_swap_b32_e32 v218, v2
	v_permlane16_swap_b32_e32 v219, v3
	v_mov_b32_e32 v220, v218
	v_mov_b32_e32 v221, v219
	v_mov_b32_e32 v222, v2
	v_mov_b32_e32 v223, v3
	v_add_co_u32_e64 v206, s[98:99], v88, v205
	s_nop 1
	v_addc_co_u32_e64 v207, s[98:99], 0, v89, s[98:99]
	global_store_dwordx4 v[206:207], v[220:223], off
	s_and_saveexec_b64 s[10:11], s[44:45]
	s_cbranch_execz .LBB0_65
	global_store_dwordx4 v[86:87], v[6:9], off offset:64
